# PRE phase: team 1's quadrant roles rotated by one wave so the two serial forward-substitution waves sit on different SIMDs
# speedup vs baseline: 1.0119x; 1.0019x over previous
.LBB0_28:
	s_and_b64 vcc, exec, s[0:1]
	s_cbranch_vccz .LBB0_643
	s_mov_b64 s[0:1], s[94:95]
	s_load_dwordx2 s[30:31], s[0:1], 0xb0
	v_mbcnt_lo_u32_b32 v180, -1, 0
	v_mbcnt_hi_u32_b32 v180, -1, v180
	v_readlane_b32 s66, v252, 3
	s_lshr_b32 s1, s66, 2
	s_add_u32 s1, s1, s66
	s_and_b32 s1, s1, 3
	s_and_b32 s66, s66, 4
	s_or_b32 s66, s66, s1
	s_lshl_b32 s42, s66, 6
	s_waitcnt vmcnt(0) lgkmcnt(0)
	v_mov_b32_e32 v3, v180
	s_movk_i32 s0, 0x440
	v_add_u32_e32 v2, s42, v3
	s_mov_b64 s[36:37], s[94:95]
	s_mov_b64 s[26:27], s[94:95]
	v_cmp_gt_i32_e32 vcc, s0, v2
	s_and_saveexec_b64 s[24:25], vcc
	s_cbranch_execz .LBB0_62
	s_load_dwordx2 s[0:1], s[36:37], 0x28
	s_load_dwordx2 s[28:29], s[26:27], 0x30
	v_readlane_b32 s26, v254, 63
	s_mul_i32 s50, s26, 0x700
	s_lshl_b64 s[36:37], s[50:51], 2
	v_readlane_b32 s27, v255, 0
	s_mov_b32 s38, s26
	s_waitcnt lgkmcnt(0)
	s_add_u32 s26, s0, s36
	s_addc_u32 s27, s1, s37
	s_add_u32 s36, s28, s36
	v_readlane_b32 s0, v255, 1
	s_addc_u32 s37, s29, s37
	v_readlane_b32 s29, v252, 16
	v_readlane_b32 s1, v255, 2
	s_mov_b32 s28, s0
	s_or_b32 s1, s28, s29
	v_and_b32_e32 v6, 63, v3
	v_or_b32_e32 v4, s1, v6
	s_lshl_b32 s1, s66, 8
	s_lshl_b32 s3, s38, 10
	v_readlane_b32 s28, v252, 17
	v_readlane_b32 s38, v252, 15
	s_add_i32 s1, s1, 0
	s_add_i32 s28, s28, s3
	s_add_i32 s3, s38, s3
	s_add_i32 s1, s1, 0x24700
	s_add_i32 s0, s29, s0
	v_mov_b32_e32 v5, v0
	v_or_b32_e32 v1, s28, v6
	v_or_b32_e32 v8, s3, v6
	v_or_b32_e32 v9, s29, v6
	v_lshl_add_u32 v10, v3, 2, s1
	s_mov_b64 s[38:39], 0
	s_branch .LBB0_32
